# attn_prep: v loads hoisted to the job top (1 round trip per job); jobs rebalanced onto the 64 workgroups without an hgrn_prep job (6 each) + 128 others (1 each)
# baseline (speedup 1.0000x reference)
; #define GAS __attribute__((address_space(1)))
; DI void attn_prep_job(const Frame& F, int job) {
;     const int bh = job >> 6, tile = job & 63, b = bh >> 2, h = bh & 3;
;     const bf16* P = (const bf16*)(F.ws + WS_P);
;     const f32x2* rope = (const f32x2*)(F.ws + WS_ROPE);
;     const int tid = F.tid;
;     {
;         const int kk = tid >> 3, c = (tid >> 2) & 1, dg = tid & 3, t = tile * 64 + kk; const size_t m = (size_t)b * SEQ + t;
;         float cs[8], sn[8];
; #pragma unroll
;         for (int i = 0; i < 8; ++i) { const f32x2 v = rope[t * 32 + 8 * dg + i]; cs[i] = v.x; sn[i] = v.y; }
;         v4u la[2], lb[2];
; #pragma unroll
;         for (int isk = 0; isk < 2; ++isk) { const bf16* src = P + m * NP + (isk ? PA_K : PA_Q) + h * 128 + c * 64 + 8 * dg; la[isk] = *(const GAS v4u*)src; lb[isk] = *(const GAS v4u*)(src + 32); }
; #pragma unroll
;         for (int isk = 0; isk < 2; ++isk) {
;             const v4u a = la[isk], bb = lb[isk];
;             float x1[8], x2[8];
;             x1[0] = bflo(a.x); x1[1] = bfhi(a.x); x1[2] = bflo(a.y); x1[3] = bfhi(a.y); x1[4] = bflo(a.z); x1[5] = bfhi(a.z); x1[6] = bflo(a.w); x1[7] = bfhi(a.w);
;             x2[0] = bflo(bb.x); x2[1] = bfhi(bb.x); x2[2] = bflo(bb.y); x2[3] = bfhi(bb.y); x2[4] = bflo(bb.z); x2[5] = bfhi(bb.z); x2[6] = bflo(bb.w); x2[7] = bfhi(bb.w);
;             const float sc = isk ? 1.0f : 0.125f * 1.4426950408889634f;
;             float o1[8], o2[8];
; #pragma unroll
;             for (int i = 0; i < 8; ++i) { o1[i] = (x1[i] * cs[i] - x2[i] * sn[i]) * sc; o2[i] = (x2[i] * cs[i] + x1[i] * sn[i]) * sc; }
;             v4u w1, w2; w1.x = pk2(o1[0], o1[1]); w1.y = pk2(o1[2], o1[3]); w1.z = pk2(o1[4], o1[5]); w1.w = pk2(o1[6], o1[7]);
;             w2.x = pk2(o2[0], o2[1]); w2.y = pk2(o2[2], o2[3]); w2.z = pk2(o2[4], o2[5]); w2.w = pk2(o2[6], o2[7]);
;             if (!isk) {
;                 bf16* q = (bf16*)(F.ws + WS_QR) + (((size_t)bh * 2 + c) * SEQ + t) * 64 + 8 * dg;
;                 *(GAS v4u*)q = w1; *(GAS v4u*)(q + 32) = w2;
;             } else {
;                 unsigned char* kf = F.ws + WS_KF + (((size_t)bh * 2 + c) * 64 + tile) * 8192;
;                 const int kvb = kk >> 5, r32 = kk & 31;
;                 const int d1 = 8 * dg, d2 = 32 + 8 * dg;
;                 *(GAS v4u*)(kf + ((kvb * 4 + (d1 >> 4)) * 64 + r32 + 32 * ((d1 >> 3) & 1)) * 16) = w1;
.LBB0_812:
	s_barrier
	v_mbcnt_lo_u32_b32 v0, -1, 0
	v_mbcnt_hi_u32_b32 v0, -1, v0
	s_mov_b64 s[0:1], s[86:87]
	v_add_u32_e32 v9, s81, v0
	s_mov_b64 s[30:31], s[84:85]
	v_readlane_b32 s82, v252, 7
	v_readlane_b32 s34, v253, 36
	v_readlane_b32 s83, v252, 8
	v_readlane_b32 s35, v253, 37
	s_mov_b64 s[30:31], s[82:83]
	s_and_b64 vcc, exec, s[34:35]
	v_readlane_b32 s95, v255, 16
	v_readlane_b32 s50, v253, 40
	v_readlane_b32 s51, v254, 1
	s_mov_b32 s52, 0x2aaaaaab
	s_mov_b32 s80, 0x4b800000
	s_mov_b32 s53, 0x60000
	s_movk_i32 s78, 0x1fff
	s_mov_b32 s54, 0x3e38aa3b
	s_mov_b64 s[56:57], 0x32503600
	s_cbranch_vccz .LBB0_815
	v_ashrrev_i32_e32 v11, 3, v9
	v_lshlrev_b32_e32 v1, 5, v9
	v_and_b32_e32 v6, 0xfffff00, v9
	v_and_b32_e32 v0, 31, v11
	v_and_b32_e32 v5, 64, v1
	v_and_or_b32 v1, v1, 32, v6
	v_and_b32_e32 v2, 3, v9
	v_or3_b32 v0, v1, v0, v5
	v_bfe_u32 v3, v9, 2, 1
	v_lshlrev_b32_e32 v0, 4, v0
	v_lshlrev_b32_e32 v96, 4, v2
	v_lshlrev_b32_e32 v8, 3, v2
	v_lshlrev_b32_e32 v10, 6, v3
	v_ashrrev_i32_e32 v1, 31, v0
	v_lshlrev_b32_e32 v12, 12, v3
	v_lshl_add_u64 v[2:3], s[0:1], 0, v[96:97]
	s_mov_b64 s[38:39], 0x3be90000
	v_lshl_add_u64 v[14:15], v[2:3], 0, s[38:39]
	v_lshl_add_u64 v[0:1], s[0:1], 0, v[0:1]
	s_mov_b64 s[38:39], 0x3c690000
	v_lshrrev_b32_e32 v2, 5, v9
	v_lshl_add_u64 v[16:17], v[0:1], 0, s[38:39]
	v_lshrrev_b32_e32 v1, 4, v9
	v_and_b32_e32 v2, 4, v2
	v_and_or_b32 v13, v1, 16, v2
	v_ashrrev_i32_e32 v2, 4, v9
	v_and_b32_e32 v18, 0xffffffe0, v2
	v_add_u32_e32 v2, 0x200, v9
	v_ashrrev_i32_e32 v2, 4, v2
	s_add_u32 s34, s0, 0x3bd80000
	v_lshrrev_b32_e32 v4, 2, v9
	v_and_b32_e32 v20, 0xffffffe0, v2
	v_and_b32_e32 v2, 31, v9
	s_movk_i32 s2, 0x60
	s_addc_u32 s35, s1, 0
	v_and_b32_e32 v1, 6, v1
	v_and_or_b32 v2, v4, s2, v2
	v_lshrrev_b32_e32 v3, 9, v9
	s_add_u32 s40, s0, 0x32500000
	v_add_u32_e32 v1, v1, v3
	v_lshlrev_b32_e32 v2, 4, v2
	s_addc_u32 s41, s1, 0
	v_lshl_or_b32 v22, v1, 11, v2
	s_add_u32 s36, s0, 0x3ce90000
	v_and_b32_e32 v0, 0x7f, v9
	v_add_u32_e32 v24, 0x800, v22
	s_addc_u32 s38, s1, 0
	v_ashrrev_i32_e32 v19, 31, v18
	v_ashrrev_i32_e32 v21, 31, v20
	v_ashrrev_i32_e32 v23, 31, v22
	v_ashrrev_i32_e32 v25, 31, v24
	v_lshlrev_b32_e32 v26, 1, v0
	v_readlane_b32 s39, v252, 2
	s_movk_i32 s98, 64
	s_movk_i32 s99, 0x180
	s_sub_i32 s39, s39, 0xc0
	s_cmp_ge_i32 s39, 0
	s_cbranch_scc1 .Lap_go
	s_add_i32 s39, s39, 0x240
	s_movk_i32 s98, 0x400
	s_movk_i32 s99, 0x200
	s_cmp_lt_i32 s39, s99
	s_cbranch_scc0 .LBB0_815
.Lap_go:
.LBB0_814:
	s_and_b32 s46, s39, 63
	s_lshl_b32 s47, s46, 6
	v_add_u32_e32 v6, s47, v11
	s_ashr_i32 s42, s39, 8
	v_lshl_or_b32 v0, v6, 5, v8
	s_ashr_i32 s43, s42, 31
	v_ashrrev_i32_e32 v1, 31, v0
	v_ashrrev_i32_e32 v7, 31, v6
	v_lshl_add_u64 v[4:5], v[0:1], 3, s[34:35]
	s_lshl_b64 s[42:43], s[42:43], 12
	flat_load_dwordx4 v[0:3], v[4:5]
	flat_load_dwordx4 v[28:31], v[4:5] offset:16
	flat_load_dwordx4 v[32:35], v[4:5] offset:32
	flat_load_dwordx4 v[36:39], v[4:5] offset:48
	s_ashr_i32 s44, s39, 6
	v_lshl_add_u64 v[40:41], s[42:43], 0, v[6:7]
	v_mov_b64_e32 v[4:5], s[40:41]
	v_mad_u64_u32 v[42:43], s[48:49], v40, s97, v[4:5]
	s_lshl_b32 s2, s44, 8
	v_mad_i32_i24 v43, v41, s97, v43
	s_and_b32 s2, s2, 0x300
	s_ashr_i32 s45, s44, 31
	v_lshl_add_u64 v[40:41], v[42:43], 0, s[2:3]
	v_lshlrev_b32_e32 v96, 1, v10
	s_lshl_b64 s[48:49], s[44:45], 7
	v_lshl_add_u64 v[40:41], v[40:41], 0, v[96:97]
	v_lshlrev_b32_e32 v96, 1, v8
	s_or_b32 s48, s48, s46
	v_lshl_add_u64 v[52:53], v[40:41], 0, v[96:97]
	v_mov_b32_e32 v49, s49
	v_or_b32_e32 v48, s48, v10
	global_load_dwordx4 v[40:43], v[52:53], off offset:1024
	global_load_dwordx4 v[44:47], v[52:53], off offset:1088
	v_lshlrev_b64 v[56:57], 13, v[48:49]
	global_load_dwordx4 v[48:51], v[52:53], off offset:64
	s_nop 0
	global_load_dwordx4 v[52:55], v[52:53], off
	s_lshl_b64 s[48:49], s[44:45], 13
	v_mov_b32_e32 v27, v97
	v_mov_b32_e32 v119, s43
	v_or_b32_e32 v118, s47, v13
	v_or_b32_e32 v118, s42, v118
	v_lshl_add_u64 v[120:121], v[118:119], 0, v[18:19]
	v_mad_u64_u32 v[122:123], s[100:101], v120, s97, v[4:5]
	v_mad_i32_i24 v123, v121, s97, v123
	v_lshl_add_u64 v[122:123], v[122:123], 0, s[2:3]
	v_lshl_add_u64 v[124:125], v[122:123], 0, v[26:27]
	v_lshl_add_u64 v[120:121], v[118:119], 0, v[20:21]
	v_mad_u64_u32 v[122:123], s[100:101], v120, s97, v[4:5]
	v_mad_i32_i24 v123, v121, s97, v123
	v_lshl_add_u64 v[122:123], v[122:123], 0, s[2:3]
	v_lshl_add_u64 v[126:127], v[122:123], 0, v[26:27]
	v_mov_b32_e32 v129, v97
	global_load_ushort v102, v[124:125], off offset:2048
	global_load_ushort v110, v[126:127], off offset:2048
	v_mov_b32_e32 v128, s4
	v_lshl_add_u64 v[130:131], v[124:125], 0, v[128:129]
	v_lshl_add_u64 v[132:133], v[126:127], 0, v[128:129]
	global_load_ushort v103, v[130:131], off offset:1024
	global_load_ushort v111, v[132:133], off offset:1024
	v_mov_b32_e32 v128, s88
	v_lshl_add_u64 v[130:131], v[124:125], 0, v[128:129]
	v_lshl_add_u64 v[132:133], v[126:127], 0, v[128:129]
	global_load_ushort v104, v[130:131], off
	global_load_ushort v112, v[132:133], off
	v_mov_b32_e32 v128, s15
	v_lshl_add_u64 v[130:131], v[124:125], 0, v[128:129]
	v_lshl_add_u64 v[132:133], v[126:127], 0, v[128:129]
	global_load_ushort v105, v[130:131], off offset:3072
	global_load_ushort v113, v[132:133], off offset:3072
	v_mov_b32_e32 v128, s89
	v_lshl_add_u64 v[130:131], v[124:125], 0, v[128:129]
	v_lshl_add_u64 v[132:133], v[126:127], 0, v[128:129]
	global_load_ushort v106, v[130:131], off offset:2048
	global_load_ushort v114, v[132:133], off offset:2048
	v_mov_b32_e32 v128, s16
	v_lshl_add_u64 v[130:131], v[124:125], 0, v[128:129]
	v_lshl_add_u64 v[132:133], v[126:127], 0, v[128:129]
	global_load_ushort v107, v[130:131], off offset:1024
	global_load_ushort v115, v[132:133], off offset:1024
	v_mov_b32_e32 v128, s6
	v_lshl_add_u64 v[130:131], v[124:125], 0, v[128:129]
	v_lshl_add_u64 v[132:133], v[126:127], 0, v[128:129]
	global_load_ushort v108, v[130:131], off
	global_load_ushort v116, v[132:133], off
	v_mov_b32_e32 v128, s18
	v_lshl_add_u64 v[130:131], v[124:125], 0, v[128:129]
	v_lshl_add_u64 v[132:133], v[126:127], 0, v[128:129]
	global_load_ushort v109, v[130:131], off offset:3072
	global_load_ushort v117, v[132:133], off offset:3072
	s_waitcnt vmcnt(0) lgkmcnt(0)
; DI void attn_prep_job(const Frame& F, int job) {
;     ...
; #pragma unroll
;         for (int isk = 0; isk < 2; ++isk) {
;             const v4u a = la[isk], bb = lb[isk];
;             float x1[8], x2[8];
;             x1[0] = bflo(a.x); x1[1] = bfhi(a.x); x1[2] = bflo(a.y); x1[3] = bfhi(a.y); x1[4] = bflo(a.z); x1[5] = bfhi(a.z); x1[6] = bflo(a.w); x1[7] = bfhi(a.w);
;             x2[0] = bflo(bb.x); x2[1] = bfhi(bb.x); x2[2] = bflo(bb.y); x2[3] = bfhi(bb.y); x2[4] = bflo(bb.z); x2[5] = bfhi(bb.z); x2[6] = bflo(bb.w); x2[7] = bfhi(bb.w);
;             const float sc = isk ? 1.0f : 0.125f * 1.4426950408889634f;
;             float o1[8], o2[8];
; #pragma unroll
;             for (int i = 0; i < 8; ++i) { o1[i] = (x1[i] * cs[i] - x2[i] * sn[i]) * sc; o2[i] = (x2[i] * cs[i] + x1[i] * sn[i]) * sc; }
;             v4u w1, w2; w1.x = pk2(o1[0], o1[1]); w1.y = pk2(o1[2], o1[3]); w1.z = pk2(o1[4], o1[5]); w1.w = pk2(o1[6], o1[7]);
;             w2.x = pk2(o2[0], o2[1]); w2.y = pk2(o2[2], o2[3]); w2.z = pk2(o2[4], o2[5]); w2.w = pk2(o2[6], o2[7]);
;             if (!isk) {
;                 bf16* q = (bf16*)(F.ws + WS_QR) + (((size_t)bh * 2 + c) * SEQ + t) * 64 + 8 * dg;
;                 *(GAS v4u*)q = w1; *(GAS v4u*)(q + 32) = w2;
;             } else {
;                 unsigned char* kf = F.ws + WS_KF + (((size_t)bh * 2 + c) * 64 + tile) * 8192;
;                 const int kvb = kk >> 5, r32 = kk & 31;
;                 const int d1 = 8 * dg, d2 = 32 + 8 * dg;
;                 *(GAS v4u*)(kf + ((kvb * 4 + (d1 >> 4)) * 64 + r32 + 32 * ((d1 >> 3) & 1)) * 16) = w1;
;                 *(GAS v4u*)(kf + ((kvb * 4 + (d2 >> 4)) * 64 + r32 + 32 * ((d2 >> 3) & 1)) * 16) = w2;
;             }
;         }
;     }
;     {
;         unsigned char* vf = F.ws + WS_VF + ((size_t)bh * 64 + tile) * 16384;
;         unsigned short ev[2][8];
; #pragma unroll
;         for (int rep = 0; rep < 2; ++rep) {
;             const int task = tid + 512 * rep, dv = task & 127, grp = task >> 7, kb = grp >> 2, s = (grp >> 1) & 1, hh = grp & 1;
;             const GAS bf16* src = (const GAS bf16*)(P + ((size_t)b * SEQ + tile * 64 + 32 * kb + 16 * s + 4 * hh) * NP + PA_V + h * 128 + dv);
; #pragma unroll
;             for (int j = 0; j < 8; ++j) ev[rep][j] = src[(size_t)(8 * (j >> 2) + (j & 3)) * NP];
;         }
; #pragma unroll
;         for (int rep = 0; rep < 2; ++rep) {
	v_mov_b32_e32 v63, v2
	v_mov_b32_e32 v2, v1
	v_mov_b32_e32 v62, v0
	v_mov_b32_e32 v67, v34
	v_mov_b32_e32 v34, v33
	v_mov_b32_e32 v66, v32
	v_mov_b32_e32 v71, v38
	v_mov_b32_e32 v38, v37
	v_mov_b32_e32 v70, v36
	v_lshlrev_b32_e32 v58, 16, v48
	v_lshlrev_b32_e32 v60, 16, v52
	v_and_b32_e32 v61, 0xffff0000, v52
	v_and_b32_e32 v59, 0xffff0000, v48
	v_pk_mul_f32 v[0:1], v[2:3], v[60:61]
	v_lshlrev_b32_e32 v52, 16, v53
	v_pk_fma_f32 v[0:1], v[62:63], v[58:59], v[0:1]
	v_pk_mul_f32 v[58:59], v[2:3], v[58:59]
	v_and_b32_e32 v53, 0xffff0000, v53
	v_pk_fma_f32 v[58:59], v[62:63], v[60:61], v[58:59] neg_lo:[0,0,1] neg_hi:[0,0,1]
	v_mov_b32_e32 v61, v30
	v_mov_b32_e32 v30, v29
	v_lshlrev_b32_e32 v48, 16, v49
	v_and_b32_e32 v49, 0xffff0000, v49
	v_mov_b32_e32 v60, v28
	v_pk_mul_f32 v[28:29], v[30:31], v[52:53]
	v_pk_mul_f32 v[0:1], v[0:1], s[54:55] op_sel_hi:[1,0]
	v_pk_fma_f32 v[28:29], v[60:61], v[48:49], v[28:29]
	v_pk_mul_f32 v[48:49], v[30:31], v[48:49]
	v_pk_mul_f32 v[58:59], v[58:59], s[54:55] op_sel_hi:[1,0]
	v_pk_fma_f32 v[48:49], v[60:61], v[52:53], v[48:49] neg_lo:[0,0,1] neg_hi:[0,0,1]
	v_lshlrev_b32_e32 v52, 16, v54
	v_and_b32_e32 v53, 0xffff0000, v54
	v_pk_mul_f32 v[64:65], v[48:49], s[54:55] op_sel_hi:[1,0]
	v_lshlrev_b32_e32 v48, 16, v50
	v_and_b32_e32 v49, 0xffff0000, v50
	v_pk_mul_f32 v[32:33], v[34:35], v[52:53]
	v_lshlrev_b32_e32 v50, 16, v55
	v_pk_fma_f32 v[32:33], v[66:67], v[48:49], v[32:33]
	v_pk_mul_f32 v[48:49], v[34:35], v[48:49]
	v_pk_mul_f32 v[28:29], v[28:29], s[54:55] op_sel_hi:[1,0]
	v_pk_fma_f32 v[48:49], v[66:67], v[52:53], v[48:49] neg_lo:[0,0,1] neg_hi:[0,0,1]
	v_pk_mul_f32 v[32:33], v[32:33], s[54:55] op_sel_hi:[1,0]
	v_pk_mul_f32 v[68:69], v[48:49], s[54:55] op_sel_hi:[1,0]
	v_lshlrev_b32_e32 v48, 16, v51
	v_and_b32_e32 v49, 0xffff0000, v51
	v_and_b32_e32 v51, 0xffff0000, v55
	v_pk_mul_f32 v[36:37], v[38:39], v[50:51]
	v_cvt_pk_bf16_f32 v52, v58, v59
	v_pk_fma_f32 v[36:37], v[70:71], v[48:49], v[36:37]
	v_pk_mul_f32 v[48:49], v[38:39], v[48:49]
	v_pk_mul_f32 v[36:37], v[36:37], s[54:55] op_sel_hi:[1,0]
	v_pk_fma_f32 v[48:49], v[70:71], v[50:51], v[48:49] neg_lo:[0,0,1] neg_hi:[0,0,1]
	v_cvt_pk_bf16_f32 v53, v64, v65
	v_pk_mul_f32 v[72:73], v[48:49], s[54:55] op_sel_hi:[1,0]
	v_cvt_pk_bf16_f32 v48, v0, v1
	v_mov_b32_e32 v1, s49
	v_or_b32_e32 v0, s48, v12
	v_lshl_add_u64 v[0:1], v[0:1], 0, v[6:7]
	v_lshlrev_b64 v[0:1], 7, v[0:1]
	v_cvt_pk_bf16_f32 v54, v68, v69
	v_cvt_pk_bf16_f32 v55, v72, v73
	v_lshl_add_u64 v[0:1], v[14:15], 0, v[0:1]
	v_lshlrev_b32_e32 v6, 16, v44
	v_and_b32_e32 v7, 0xffff0000, v44
	v_cvt_pk_bf16_f32 v49, v28, v29
	v_cvt_pk_bf16_f32 v50, v32, v33
	v_cvt_pk_bf16_f32 v51, v36, v37
	global_store_dwordx4 v[0:1], v[52:55], off
	global_store_dwordx4 v[0:1], v[48:51], off offset:64
	v_lshlrev_b32_e32 v28, 16, v40
	v_and_b32_e32 v29, 0xffff0000, v40
	v_pk_mul_f32 v[0:1], v[62:63], v[6:7]
	s_lshl_b64 s[48:49], s[44:45], 20
	v_pk_fma_f32 v[0:1], v[2:3], v[28:29], v[0:1]
	v_pk_mul_f32 v[2:3], v[2:3], v[6:7]
	v_lshlrev_b32_e32 v6, 16, v41
	v_pk_fma_f32 v[2:3], v[62:63], v[28:29], v[2:3] neg_lo:[0,0,1] neg_hi:[0,0,1]
	v_and_b32_e32 v7, 0xffff0000, v41
	v_cvt_pk_bf16_f32 v28, v2, v3
	v_lshlrev_b32_e32 v2, 16, v45
	v_and_b32_e32 v3, 0xffff0000, v45
	v_pk_mul_f32 v[32:33], v[60:61], v[2:3]
	v_pk_mul_f32 v[2:3], v[30:31], v[2:3]
	v_pk_fma_f32 v[32:33], v[30:31], v[6:7], v[32:33]
	v_pk_fma_f32 v[2:3], v[60:61], v[6:7], v[2:3] neg_lo:[0,0,1] neg_hi:[0,0,1]
	v_lshlrev_b32_e32 v6, 16, v46
	v_and_b32_e32 v7, 0xffff0000, v46
	v_cvt_pk_bf16_f32 v29, v2, v3
	v_lshlrev_b32_e32 v30, 16, v42
	v_and_b32_e32 v31, 0xffff0000, v42
	v_pk_mul_f32 v[2:3], v[66:67], v[6:7]
	v_pk_mul_f32 v[6:7], v[34:35], v[6:7]
	v_pk_fma_f32 v[2:3], v[34:35], v[30:31], v[2:3]
	v_pk_fma_f32 v[6:7], v[66:67], v[30:31], v[6:7] neg_lo:[0,0,1] neg_hi:[0,0,1]
	v_cvt_pk_bf16_f32 v0, v0, v1
	v_cvt_pk_bf16_f32 v30, v6, v7
	v_lshlrev_b32_e32 v6, 16, v47
	v_and_b32_e32 v7, 0xffff0000, v47
	v_cvt_pk_bf16_f32 v1, v32, v33
	v_lshlrev_b32_e32 v32, 16, v43
	v_and_b32_e32 v33, 0xffff0000, v43
	v_pk_mul_f32 v[34:35], v[70:71], v[6:7]
	v_pk_mul_f32 v[6:7], v[38:39], v[6:7]
	v_pk_fma_f32 v[34:35], v[38:39], v[32:33], v[34:35]
	v_pk_fma_f32 v[6:7], v[70:71], v[32:33], v[6:7] neg_lo:[0,0,1] neg_hi:[0,0,1]
	v_cvt_pk_bf16_f32 v2, v2, v3
	v_cvt_pk_bf16_f32 v31, v6, v7
	v_lshl_add_u64 v[6:7], v[16:17], 0, v[56:57]
	v_cvt_pk_bf16_f32 v3, v34, v35
	global_store_dwordx4 v[6:7], v[28:31], off
	global_store_dwordx4 v[6:7], v[0:3], off offset:2048
	s_lshl_b32 s44, s46, 14
	s_add_u32 s45, s36, s48
	s_addc_u32 s46, s38, s49
	s_add_u32 s42, s45, s44
	s_addc_u32 s43, s46, 0
	s_add_i32 s39, s39, s98
	v_lshl_add_u64 v[28:29], s[42:43], 0, v[22:23]
	v_lshl_add_u64 v[30:31], s[42:43], 0, v[24:25]
	v_lshl_or_b32 v0, v103, 16, v102
	v_lshl_or_b32 v1, v105, 16, v104
	v_lshl_or_b32 v2, v107, 16, v106
	v_lshl_or_b32 v3, v109, 16, v108
	v_lshl_or_b32 v4, v111, 16, v110
	v_lshl_or_b32 v5, v113, 16, v112
	v_lshl_or_b32 v6, v115, 16, v114
	v_lshl_or_b32 v7, v117, 16, v116
	s_cmp_lt_i32 s39, s99
	global_store_dwordx4 v[28:29], v[0:3], off
	global_store_dwordx4 v[30:31], v[4:7], off
	s_cbranch_scc1 .LBB0_814
